# nt hint on final output stores of the out GEMM
# baseline (speedup 1.0000x reference)
; #define PG8_STAGE(bufoff, gbase, voff) do { _Pragma("unroll") for (int _i = 0; _i < 2; ++_i) \
;         __builtin_amdgcn_global_load_lds((const unsigned*)((const char*)(gbase) + (voff)[_i]), (LAS unsigned*)(lds + (bufoff) + ldsw + _i * 8192), 16, 0, 0); } while (0)
; #define PG8_LDA(dst, b, h) do { _Pragma("unroll") for (int m = 0; m < 4; ++m) _Pragma("unroll") for (int k = 0; k < 2; ++k) dst[m][k] = *(const LAS bf16x8*)(lds + PG8_SA(b, h) + aoff + m * 2048 + k * 1024); } while (0)
; #define PG8_LDB(dst, b, h) do { _Pragma("unroll") for (int n = 0; n < 2; ++n) _Pragma("unroll") for (int k = 0; k < 2; ++k) dst[n][k] = *(const LAS bf16x8*)(lds + PG8_SB(b, h) + boff + n * 2048 + k * 1024); } while (0)
; #define PG8_MMA(ai, bj, At, Bt) do { __builtin_amdgcn_s_setprio(1); _Pragma("unroll") for (int m = 0; m < 4; ++m) _Pragma("unroll") for (int n = 0; n < 2; ++n) _Pragma("unroll") for (int k = 0; k < 2; ++k) \
;         acc[ai][bj][m][n] = __builtin_amdgcn_mfma_f32_16x16x32_bf16(Bt[n][k], At[m][k], acc[ai][bj][m][n], 0, 0, 0); __builtin_amdgcn_s_setprio(0); } while (0)
; #define PG8_WAIT_V(n) asm volatile("s_waitcnt vmcnt(" #n ")" ::: "memory")
; #define PG8_WAIT_L(n) asm volatile("s_waitcnt lgkmcnt(" #n ")" ::: "memory")
; #define PG8_BAR __builtin_amdgcn_s_barrier()
; #define PG8_SCHED __builtin_amdgcn_sched_barrier(0)
; template <class Epi>
; DI void gemm_phase(LAS unsigned char* lds, const Gemm g, const StaticOrder& S, const Epi& E) {
;     ...
;             PG8_LDB(B0, 0, 0); PG8_SCHED; PG8_LDA(At, 0, 0); PG8_STAGE(PG8_SA(1, 1), a1 + hstepA, voffA);
;             PG8_WAIT_L(8); PG8_BAR; PG8_WAIT_L(0); PG8_MMA(0, 0, At, B0); PG8_BAR; PG8_SCHED;
;             PG8_LDB(B1, 0, 1); PG8_STAGE(PG8_SB(0, 0), b2, voffB);
;             PG8_BAR; PG8_WAIT_L(0); PG8_MMA(0, 1, At, B1); PG8_BAR;
;             PG8_LDA(At, 0, 1); PG8_STAGE(PG8_SA(0, 0), a2, voffA);
;             PG8_BAR; PG8_WAIT_L(0); PG8_MMA(1, 0, At, B0); PG8_BAR; PG8_SCHED;
;             PG8_STAGE(PG8_SB(0, 1), b2 + hstepB, voffB);
;             PG8_WAIT_V(6); PG8_BAR; PG8_MMA(1, 1, At, B1); PG8_BAR;
.LBB0_705:
	ds_read_b128 v[144:147], v153
	ds_read_b128 v[156:159], v153 offset:1024
	ds_read_b128 v[160:163], v153 offset:2048
	ds_read_b128 v[164:167], v153 offset:3072
	s_add_u32 s2, s26, 0x100
	s_addc_u32 s3, s27, 0
	s_cmp_eq_u32 s56, 28
	s_cselect_b32 s37, s23, s3
	s_cselect_b32 s36, s22, s2
	s_cselect_b32 s35, s21, s55
	s_cselect_b32 s34, s53, s54
	v_lshl_add_u64 v[148:149], s[26:27], 0, v[136:137]
	s_add_i32 m0, s40, 0xc000
	ds_read_b128 v[168:171], v154
	ds_read_b128 v[172:175], v154 offset:1024
	ds_read_b128 v[176:179], v154 offset:2048
	ds_read_b128 v[180:183], v154 offset:3072
	ds_read_b128 v[184:187], v154 offset:4096
	ds_read_b128 v[188:191], v154 offset:5120
	ds_read_b128 v[192:195], v154 offset:6144
	ds_read_b128 v[196:199], v154 offset:7168
	global_load_lds_dwordx4 v[148:149], off
	v_lshl_add_u64 v[148:149], s[26:27], 0, v[138:139]
	s_add_i32 m0, s40, 0xe000
	s_nop 0
	global_load_lds_dwordx4 v[148:149], off
	s_waitcnt lgkmcnt(8)
	s_barrier
	s_waitcnt lgkmcnt(0)
	s_setprio 1
	s_waitcnt lgkmcnt(0)
	v_mfma_f32_16x16x32_bf16 v[124:127], v[144:147], v[168:171], v[124:127]
	v_mfma_f32_16x16x32_bf16 v[120:123], v[160:163], v[168:171], v[120:123]
	v_mfma_f32_16x16x32_bf16 v[116:119], v[144:147], v[176:179], v[116:119]
	v_mfma_f32_16x16x32_bf16 v[112:115], v[160:163], v[176:179], v[112:115]
	v_mfma_f32_16x16x32_bf16 v[108:111], v[144:147], v[184:187], v[108:111]
	v_mfma_f32_16x16x32_bf16 v[100:103], v[160:163], v[184:187], v[100:103]
	v_mfma_f32_16x16x32_bf16 v[92:95], v[144:147], v[192:195], v[92:95]
	v_mfma_f32_16x16x32_bf16 v[80:83], v[160:163], v[192:195], v[80:83]
	v_mfma_f32_16x16x32_bf16 v[124:127], v[156:159], v[172:175], v[124:127]
	v_mfma_f32_16x16x32_bf16 v[120:123], v[164:167], v[172:175], v[120:123]
	v_mfma_f32_16x16x32_bf16 v[116:119], v[156:159], v[180:183], v[116:119]
	v_mfma_f32_16x16x32_bf16 v[112:115], v[164:167], v[180:183], v[112:115]
	v_mfma_f32_16x16x32_bf16 v[108:111], v[156:159], v[188:191], v[108:111]
	v_mfma_f32_16x16x32_bf16 v[100:103], v[164:167], v[188:191], v[100:103]
	v_mfma_f32_16x16x32_bf16 v[92:95], v[156:159], v[196:199], v[92:95]
	v_mfma_f32_16x16x32_bf16 v[80:83], v[164:167], v[196:199], v[80:83]
	s_setprio 0
	s_barrier
	s_add_i32 s26, s48, s39
	v_lshl_add_u64 v[148:149], s[34:35], 0, v[130:131]
	s_mov_b32 m0, s26
	ds_read_b128 v[200:203], v155
	ds_read_b128 v[204:207], v155 offset:1024
	ds_read_b128 v[208:211], v155 offset:2048
	ds_read_b128 v[212:215], v155 offset:3072
	global_load_lds_dwordx4 v[148:149], off
	v_lshl_add_u64 v[216:217], s[34:35], 0, v[134:135]
	s_add_i32 m0, s26, 0x2000
	s_nop 0
	global_load_lds_dwordx4 v[216:217], off
	s_barrier
	s_waitcnt lgkmcnt(0)
	s_setprio 1
	s_waitcnt lgkmcnt(0)
	v_mfma_f32_16x16x32_bf16 v[104:107], v[200:203], v[168:171], v[104:107]
	v_mfma_f32_16x16x32_bf16 v[96:99], v[208:211], v[168:171], v[96:99]
	v_mfma_f32_16x16x32_bf16 v[88:91], v[200:203], v[176:179], v[88:91]
	v_mfma_f32_16x16x32_bf16 v[84:87], v[208:211], v[176:179], v[84:87]
	v_mfma_f32_16x16x32_bf16 v[76:79], v[200:203], v[184:187], v[76:79]
	v_mfma_f32_16x16x32_bf16 v[72:75], v[208:211], v[184:187], v[72:75]
	v_mfma_f32_16x16x32_bf16 v[68:71], v[200:203], v[192:195], v[68:71]
	v_mfma_f32_16x16x32_bf16 v[64:67], v[208:211], v[192:195], v[64:67]
	v_mfma_f32_16x16x32_bf16 v[104:107], v[204:207], v[172:175], v[104:107]
	v_mfma_f32_16x16x32_bf16 v[96:99], v[212:215], v[172:175], v[96:99]
	v_mfma_f32_16x16x32_bf16 v[88:91], v[204:207], v[180:183], v[88:91]
	v_mfma_f32_16x16x32_bf16 v[84:87], v[212:215], v[180:183], v[84:87]
	v_mfma_f32_16x16x32_bf16 v[76:79], v[204:207], v[188:191], v[76:79]
	v_mfma_f32_16x16x32_bf16 v[72:75], v[212:215], v[188:191], v[72:75]
	v_mfma_f32_16x16x32_bf16 v[68:71], v[204:207], v[196:199], v[68:71]
	v_mfma_f32_16x16x32_bf16 v[64:67], v[212:215], v[196:199], v[64:67]
	s_setprio 0
	s_mov_b32 m0, s40
	v_lshl_add_u64 v[218:219], s[36:37], 0, v[128:129]
	s_barrier
	ds_read_b128 v[168:171], v154 offset:16384
	ds_read_b128 v[172:175], v154 offset:17408
	ds_read_b128 v[176:179], v154 offset:18432
	ds_read_b128 v[180:183], v154 offset:19456
	ds_read_b128 v[184:187], v154 offset:20480
	ds_read_b128 v[188:191], v154 offset:21504
	ds_read_b128 v[192:195], v154 offset:22528
	ds_read_b128 v[196:199], v154 offset:23552
	global_load_lds_dwordx4 v[218:219], off
	v_lshl_add_u64 v[220:221], s[36:37], 0, v[132:133]
	s_mov_b32 m0, s41
	s_nop 0
	global_load_lds_dwordx4 v[220:221], off
	s_barrier
	s_waitcnt lgkmcnt(0)
	s_setprio 1
	s_waitcnt lgkmcnt(0)
	v_mfma_f32_16x16x32_bf16 v[60:63], v[144:147], v[168:171], v[60:63]
	v_mfma_f32_16x16x32_bf16 v[56:59], v[160:163], v[168:171], v[56:59]
	v_mfma_f32_16x16x32_bf16 v[52:55], v[144:147], v[176:179], v[52:55]
	v_mfma_f32_16x16x32_bf16 v[48:51], v[160:163], v[176:179], v[48:51]
	v_mfma_f32_16x16x32_bf16 v[44:47], v[144:147], v[184:187], v[44:47]
	v_mfma_f32_16x16x32_bf16 v[36:39], v[160:163], v[184:187], v[36:39]
	v_mfma_f32_16x16x32_bf16 v[28:31], v[144:147], v[192:195], v[28:31]
	v_mfma_f32_16x16x32_bf16 v[16:19], v[160:163], v[192:195], v[16:19]
	v_mfma_f32_16x16x32_bf16 v[60:63], v[156:159], v[172:175], v[60:63]
	v_mfma_f32_16x16x32_bf16 v[56:59], v[164:167], v[172:175], v[56:59]
	v_mfma_f32_16x16x32_bf16 v[52:55], v[156:159], v[180:183], v[52:55]
	v_mfma_f32_16x16x32_bf16 v[48:51], v[164:167], v[180:183], v[48:51]
	v_mfma_f32_16x16x32_bf16 v[44:47], v[156:159], v[188:191], v[44:47]
	v_mfma_f32_16x16x32_bf16 v[36:39], v[164:167], v[188:191], v[36:39]
	v_mfma_f32_16x16x32_bf16 v[28:31], v[156:159], v[196:199], v[28:31]
	v_mfma_f32_16x16x32_bf16 v[16:19], v[164:167], v[196:199], v[16:19]
	s_setprio 0
	s_barrier
; #define PG8_STAGE(bufoff, gbase, voff) do { _Pragma("unroll") for (int _i = 0; _i < 2; ++_i) \
;         __builtin_amdgcn_global_load_lds((const unsigned*)((const char*)(gbase) + (voff)[_i]), (LAS unsigned*)(lds + (bufoff) + ldsw + _i * 8192), 16, 0, 0); } while (0)
; #define PG8_LDA(dst, b, h) do { _Pragma("unroll") for (int m = 0; m < 4; ++m) _Pragma("unroll") for (int k = 0; k < 2; ++k) dst[m][k] = *(const LAS bf16x8*)(lds + PG8_SA(b, h) + aoff + m * 2048 + k * 1024); } while (0)
; #define PG8_LDB(dst, b, h) do { _Pragma("unroll") for (int n = 0; n < 2; ++n) _Pragma("unroll") for (int k = 0; k < 2; ++k) dst[n][k] = *(const LAS bf16x8*)(lds + PG8_SB(b, h) + boff + n * 2048 + k * 1024); } while (0)
; #define PG8_MMA(ai, bj, At, Bt) do { __builtin_amdgcn_s_setprio(1); _Pragma("unroll") for (int m = 0; m < 4; ++m) _Pragma("unroll") for (int n = 0; n < 2; ++n) _Pragma("unroll") for (int k = 0; k < 2; ++k) \
;         acc[ai][bj][m][n] = __builtin_amdgcn_mfma_f32_16x16x32_bf16(Bt[n][k], At[m][k], acc[ai][bj][m][n], 0, 0, 0); __builtin_amdgcn_s_setprio(0); } while (0)
; #define PG8_WAIT_V(n) asm volatile("s_waitcnt vmcnt(" #n ")" ::: "memory")
; #define PG8_WAIT_L(n) asm volatile("s_waitcnt lgkmcnt(" #n ")" ::: "memory")
; #define PG8_BAR __builtin_amdgcn_s_barrier()
; #define PG8_SCHED __builtin_amdgcn_sched_barrier(0)
; template <class Epi>
; DI void gemm_phase(LAS unsigned char* lds, const Gemm g, const StaticOrder& S, const Epi& E) {
;     ...
;             PG8_WAIT_V(6); PG8_BAR; PG8_MMA(1, 1, At, B1); PG8_BAR;
;             PG8_LDB(B0, 1, 0); PG8_SCHED; PG8_LDA(At, 1, 0); PG8_STAGE(PG8_SA(0, 1), a2 + hstepA, voffA);
;             PG8_WAIT_L(8); PG8_BAR; PG8_WAIT_L(0); PG8_MMA(0, 0, At, B0); PG8_BAR; PG8_SCHED;
;             PG8_LDB(B1, 1, 1); PG8_STAGE(PG8_SB(1, 0), b3, voffB);
;             PG8_BAR; PG8_WAIT_L(0); PG8_MMA(0, 1, At, B1); PG8_BAR;
;             PG8_LDA(At, 1, 1); PG8_STAGE(PG8_SA(1, 0), a3, voffA);
;             PG8_BAR; PG8_WAIT_L(0); PG8_MMA(1, 0, At, B0); PG8_BAR; PG8_SCHED;
	s_add_u32 s26, s34, 0x80000
	s_addc_u32 s27, s35, 0
	s_add_i32 s57, s49, s39
	v_lshl_add_u64 v[144:145], s[26:27], 0, v[130:131]
	s_mov_b32 m0, s57
	s_nop 0
	global_load_lds_dwordx4 v[144:145], off
	v_lshl_add_u64 v[144:145], s[26:27], 0, v[134:135]
	s_add_i32 m0, s57, 0x2000
	s_nop 0
	global_load_lds_dwordx4 v[144:145], off
	s_waitcnt vmcnt(6)
	s_barrier
	s_setprio 1
	v_mfma_f32_16x16x32_bf16 v[40:43], v[200:203], v[168:171], v[40:43]
	v_mfma_f32_16x16x32_bf16 v[32:35], v[208:211], v[168:171], v[32:35]
	v_mfma_f32_16x16x32_bf16 v[24:27], v[200:203], v[176:179], v[24:27]
	v_mfma_f32_16x16x32_bf16 v[20:23], v[208:211], v[176:179], v[20:23]
	v_mfma_f32_16x16x32_bf16 v[12:15], v[200:203], v[184:187], v[12:15]
	v_mfma_f32_16x16x32_bf16 v[8:11], v[208:211], v[184:187], v[8:11]
	v_mfma_f32_16x16x32_bf16 v[4:7], v[200:203], v[192:195], v[4:7]
	v_mfma_f32_16x16x32_bf16 v[0:3], v[208:211], v[192:195], v[0:3]
	v_mfma_f32_16x16x32_bf16 v[40:43], v[204:207], v[172:175], v[40:43]
	v_mfma_f32_16x16x32_bf16 v[32:35], v[212:215], v[172:175], v[32:35]
	v_mfma_f32_16x16x32_bf16 v[24:27], v[204:207], v[180:183], v[24:27]
	v_mfma_f32_16x16x32_bf16 v[20:23], v[212:215], v[180:183], v[20:23]
	v_mfma_f32_16x16x32_bf16 v[12:15], v[204:207], v[188:191], v[12:15]
	v_mfma_f32_16x16x32_bf16 v[8:11], v[212:215], v[188:191], v[8:11]
	v_mfma_f32_16x16x32_bf16 v[4:7], v[204:207], v[196:199], v[4:7]
	v_mfma_f32_16x16x32_bf16 v[0:3], v[212:215], v[196:199], v[0:3]
	s_setprio 0
	s_add_i32 s57, 0, 0x18000
	v_add_u32_e32 v164, s57, v151
	s_barrier
	ds_read_b128 v[144:147], v164
	ds_read_b128 v[156:159], v164 offset:1024
	ds_read_b128 v[160:163], v164 offset:2048
	ds_read_b128 v[164:167], v164 offset:3072
	s_add_u32 s26, s36, 0x3b0000
	s_addc_u32 s27, s37, 0
	s_mov_b32 m0, s42
	v_lshl_add_u64 v[200:201], s[26:27], 0, v[128:129]
	ds_read_b128 v[168:171], v154 offset:32768
	ds_read_b128 v[172:175], v154 offset:33792
	ds_read_b128 v[176:179], v154 offset:34816
	ds_read_b128 v[180:183], v154 offset:35840
	ds_read_b128 v[184:187], v154 offset:36864
	ds_read_b128 v[188:191], v154 offset:37888
	ds_read_b128 v[192:195], v154 offset:38912
	ds_read_b128 v[196:199], v154 offset:39936
	global_load_lds_dwordx4 v[200:201], off
	v_lshl_add_u64 v[200:201], s[26:27], 0, v[132:133]
	s_mov_b32 m0, s43
	s_nop 0
	global_load_lds_dwordx4 v[200:201], off
	s_waitcnt lgkmcnt(8)
	s_barrier
	s_waitcnt lgkmcnt(0)
	s_setprio 1
	s_waitcnt lgkmcnt(0)
	v_mfma_f32_16x16x32_bf16 v[124:127], v[144:147], v[168:171], v[124:127]
	v_mfma_f32_16x16x32_bf16 v[120:123], v[160:163], v[168:171], v[120:123]
	v_mfma_f32_16x16x32_bf16 v[116:119], v[144:147], v[176:179], v[116:119]
	v_mfma_f32_16x16x32_bf16 v[112:115], v[160:163], v[176:179], v[112:115]
	v_mfma_f32_16x16x32_bf16 v[108:111], v[144:147], v[184:187], v[108:111]
	v_mfma_f32_16x16x32_bf16 v[100:103], v[160:163], v[184:187], v[100:103]
	v_mfma_f32_16x16x32_bf16 v[92:95], v[144:147], v[192:195], v[92:95]
	v_mfma_f32_16x16x32_bf16 v[80:83], v[160:163], v[192:195], v[80:83]
	v_mfma_f32_16x16x32_bf16 v[124:127], v[156:159], v[172:175], v[124:127]
	v_mfma_f32_16x16x32_bf16 v[120:123], v[164:167], v[172:175], v[120:123]
	v_mfma_f32_16x16x32_bf16 v[116:119], v[156:159], v[180:183], v[116:119]
	v_mfma_f32_16x16x32_bf16 v[112:115], v[164:167], v[180:183], v[112:115]
	v_mfma_f32_16x16x32_bf16 v[108:111], v[156:159], v[188:191], v[108:111]
	v_mfma_f32_16x16x32_bf16 v[100:103], v[164:167], v[188:191], v[100:103]
	v_mfma_f32_16x16x32_bf16 v[92:95], v[156:159], v[196:199], v[92:95]
	v_mfma_f32_16x16x32_bf16 v[80:83], v[164:167], v[196:199], v[80:83]
	s_setprio 0
	s_barrier
	s_add_i32 s36, 0, 0x1c000
	s_add_i32 s26, s57, s39
	v_add_u32_e32 v212, s36, v151
	v_lshl_add_u64 v[148:149], v[148:149], 0, s[4:5]
	s_mov_b32 m0, s26
	ds_read_b128 v[200:203], v212
	ds_read_b128 v[204:207], v212 offset:1024
	ds_read_b128 v[208:211], v212 offset:2048
	ds_read_b128 v[212:215], v212 offset:3072
	global_load_lds_dwordx4 v[148:149], off
	v_lshl_add_u64 v[148:149], v[216:217], 0, s[4:5]
	s_add_i32 m0, s26, 0x2000
	s_nop 0
	global_load_lds_dwordx4 v[148:149], off
	s_barrier
	s_waitcnt lgkmcnt(0)
	s_setprio 1
	s_waitcnt lgkmcnt(0)
	v_mfma_f32_16x16x32_bf16 v[104:107], v[200:203], v[168:171], v[104:107]
	v_mfma_f32_16x16x32_bf16 v[96:99], v[208:211], v[168:171], v[96:99]
	v_mfma_f32_16x16x32_bf16 v[88:91], v[200:203], v[176:179], v[88:91]
	v_mfma_f32_16x16x32_bf16 v[84:87], v[208:211], v[176:179], v[84:87]
	v_mfma_f32_16x16x32_bf16 v[76:79], v[200:203], v[184:187], v[76:79]
	v_mfma_f32_16x16x32_bf16 v[72:75], v[208:211], v[184:187], v[72:75]
	v_mfma_f32_16x16x32_bf16 v[68:71], v[200:203], v[192:195], v[68:71]
	v_mfma_f32_16x16x32_bf16 v[64:67], v[208:211], v[192:195], v[64:67]
	v_mfma_f32_16x16x32_bf16 v[104:107], v[204:207], v[172:175], v[104:107]
	v_mfma_f32_16x16x32_bf16 v[96:99], v[212:215], v[172:175], v[96:99]
	v_mfma_f32_16x16x32_bf16 v[88:91], v[204:207], v[180:183], v[88:91]
	v_mfma_f32_16x16x32_bf16 v[84:87], v[212:215], v[180:183], v[84:87]
	v_mfma_f32_16x16x32_bf16 v[76:79], v[204:207], v[188:191], v[76:79]
	v_mfma_f32_16x16x32_bf16 v[72:75], v[212:215], v[188:191], v[72:75]
	v_mfma_f32_16x16x32_bf16 v[68:71], v[204:207], v[196:199], v[68:71]
	v_mfma_f32_16x16x32_bf16 v[64:67], v[212:215], v[196:199], v[64:67]
	s_setprio 0
	s_mov_b32 m0, s45
	v_lshl_add_u64 v[148:149], v[218:219], 0, s[4:5]
	s_barrier
	ds_read_b128 v[168:171], v154 offset:49152
	ds_read_b128 v[172:175], v154 offset:50176
	ds_read_b128 v[176:179], v154 offset:51200
	ds_read_b128 v[180:183], v154 offset:52224
	ds_read_b128 v[184:187], v154 offset:53248
	ds_read_b128 v[188:191], v154 offset:54272
	ds_read_b128 v[192:195], v154 offset:55296
	ds_read_b128 v[196:199], v154 offset:56320
	global_load_lds_dwordx4 v[148:149], off
	v_lshl_add_u64 v[148:149], v[220:221], 0, s[4:5]
	s_mov_b32 m0, s46
	s_nop 0
	global_load_lds_dwordx4 v[148:149], off
	s_barrier
; #define PG8_STAGE(bufoff, gbase, voff) do { _Pragma("unroll") for (int _i = 0; _i < 2; ++_i) \
;         __builtin_amdgcn_global_load_lds((const unsigned*)((const char*)(gbase) + (voff)[_i]), (LAS unsigned*)(lds + (bufoff) + ldsw + _i * 8192), 16, 0, 0); } while (0)
; #define PG8_MMA(ai, bj, At, Bt) do { __builtin_amdgcn_s_setprio(1); _Pragma("unroll") for (int m = 0; m < 4; ++m) _Pragma("unroll") for (int n = 0; n < 2; ++n) _Pragma("unroll") for (int k = 0; k < 2; ++k) \
;         acc[ai][bj][m][n] = __builtin_amdgcn_mfma_f32_16x16x32_bf16(Bt[n][k], At[m][k], acc[ai][bj][m][n], 0, 0, 0); __builtin_amdgcn_s_setprio(0); } while (0)
; #define PG8_WAIT_V(n) asm volatile("s_waitcnt vmcnt(" #n ")" ::: "memory")
; #define PG8_WAIT_L(n) asm volatile("s_waitcnt lgkmcnt(" #n ")" ::: "memory")
; #define PG8_BAR __builtin_amdgcn_s_barrier()
; #define PG8_SCHED __builtin_amdgcn_sched_barrier(0)
; template <class Epi>
; DI void gemm_phase(LAS unsigned char* lds, const Gemm g, const StaticOrder& S, const Epi& E) {
;     ...
;             PG8_BAR; PG8_WAIT_L(0); PG8_MMA(1, 0, At, B0); PG8_BAR; PG8_SCHED;
;             PG8_STAGE(PG8_SB(1, 1), b3 + hstepB, voffB);
;             PG8_WAIT_V(6); PG8_BAR; PG8_MMA(1, 1, At, B1); PG8_BAR;
;         }
;         E(acc, cur, wr, wc, fr, fq);
;     DI void operator()(const f32x4 (&acc)[2][2][4][2], const Unit& u, int wr, int wc, int fr, int fq) const {
;     ...
;             f32x4 xv[4][2][2];
; #pragma unroll
;             for (int m = 0; m < 4; ++m) { const size_t off = (size_t)(row0 + ai * HALF + m * 16) * DM + col0;
; #pragma unroll
;                 for (int bj = 0; bj < 2; ++bj)
; #pragma unroll
;                     for (int n = 0; n < 2; ++n) xv[m][bj][n] = *(const f32x4*)(X + off + bj * HALF + n * 16); }
	s_waitcnt lgkmcnt(0)
	s_setprio 1
	s_waitcnt lgkmcnt(0)
	v_mfma_f32_16x16x32_bf16 v[60:63], v[144:147], v[168:171], v[60:63]
	v_mfma_f32_16x16x32_bf16 v[56:59], v[160:163], v[168:171], v[56:59]
	v_mfma_f32_16x16x32_bf16 v[52:55], v[144:147], v[176:179], v[52:55]
	v_mfma_f32_16x16x32_bf16 v[48:51], v[160:163], v[176:179], v[48:51]
	v_mfma_f32_16x16x32_bf16 v[44:47], v[144:147], v[184:187], v[44:47]
	v_mfma_f32_16x16x32_bf16 v[36:39], v[160:163], v[184:187], v[36:39]
	v_mfma_f32_16x16x32_bf16 v[28:31], v[144:147], v[192:195], v[28:31]
	v_mfma_f32_16x16x32_bf16 v[16:19], v[160:163], v[192:195], v[16:19]
	v_mfma_f32_16x16x32_bf16 v[60:63], v[156:159], v[172:175], v[60:63]
	v_mfma_f32_16x16x32_bf16 v[56:59], v[164:167], v[172:175], v[56:59]
	v_mfma_f32_16x16x32_bf16 v[52:55], v[156:159], v[180:183], v[52:55]
	v_mfma_f32_16x16x32_bf16 v[48:51], v[164:167], v[180:183], v[48:51]
	v_mfma_f32_16x16x32_bf16 v[44:47], v[156:159], v[188:191], v[44:47]
	v_mfma_f32_16x16x32_bf16 v[36:39], v[164:167], v[188:191], v[36:39]
	v_mfma_f32_16x16x32_bf16 v[28:31], v[156:159], v[196:199], v[28:31]
	v_mfma_f32_16x16x32_bf16 v[16:19], v[164:167], v[196:199], v[16:19]
	s_setprio 0
	s_barrier
	s_add_u32 s26, s34, 0x80080
	s_addc_u32 s27, s35, 0
	s_add_i32 s34, s36, s39
	v_lshl_add_u64 v[144:145], s[26:27], 0, v[130:131]
	s_mov_b32 m0, s34
	s_nop 0
	global_load_lds_dwordx4 v[144:145], off
	v_lshl_add_u64 v[144:145], s[26:27], 0, v[134:135]
	s_add_i32 m0, s34, 0x2000
	s_nop 0
	global_load_lds_dwordx4 v[144:145], off
	s_waitcnt vmcnt(6)
	s_barrier
	s_setprio 1
	v_mfma_f32_16x16x32_bf16 v[40:43], v[200:203], v[168:171], v[40:43]
	v_mfma_f32_16x16x32_bf16 v[32:35], v[208:211], v[168:171], v[32:35]
	v_mfma_f32_16x16x32_bf16 v[24:27], v[200:203], v[176:179], v[24:27]
	v_mfma_f32_16x16x32_bf16 v[20:23], v[208:211], v[176:179], v[20:23]
	v_mfma_f32_16x16x32_bf16 v[12:15], v[200:203], v[184:187], v[12:15]
	v_mfma_f32_16x16x32_bf16 v[8:11], v[208:211], v[184:187], v[8:11]
	v_mfma_f32_16x16x32_bf16 v[4:7], v[200:203], v[192:195], v[4:7]
	v_mfma_f32_16x16x32_bf16 v[0:3], v[208:211], v[192:195], v[0:3]
	v_mfma_f32_16x16x32_bf16 v[40:43], v[204:207], v[172:175], v[40:43]
	v_mfma_f32_16x16x32_bf16 v[32:35], v[212:215], v[172:175], v[32:35]
	v_mfma_f32_16x16x32_bf16 v[24:27], v[204:207], v[180:183], v[24:27]
	v_mfma_f32_16x16x32_bf16 v[20:23], v[212:215], v[180:183], v[20:23]
	v_mfma_f32_16x16x32_bf16 v[12:15], v[204:207], v[188:191], v[12:15]
	v_mfma_f32_16x16x32_bf16 v[8:11], v[212:215], v[188:191], v[8:11]
	v_mfma_f32_16x16x32_bf16 v[4:7], v[204:207], v[196:199], v[4:7]
	v_mfma_f32_16x16x32_bf16 v[0:3], v[212:215], v[196:199], v[0:3]
	s_setprio 0
	s_add_i32 s56, s56, 2
	s_add_u32 s54, s54, 0x100
	s_addc_u32 s55, s55, 0
	s_cmp_gt_u32 s56, 29
	s_mov_b64 s[26:27], s[2:3]
	s_barrier
	s_cbranch_scc0 .LBB0_705
	v_lshl_add_u32 v204, s51, 8, v150
	v_lshl_or_b32 v144, s52, 8, v152
	v_ashrrev_i32_e32 v205, 31, v204
	v_ashrrev_i32_e32 v145, 31, v144
	v_lshlrev_b64 v[148:149], 13, v[204:205]
	v_or_b32_e32 v172, 16, v204
	v_or_b32_e32 v188, 32, v204
	v_or_b32_e32 v204, 48, v204
	v_lshlrev_b64 v[144:145], 2, v[144:145]
	v_ashrrev_i32_e32 v173, 31, v172
	v_ashrrev_i32_e32 v189, 31, v188
	v_ashrrev_i32_e32 v205, 31, v204
	v_lshl_add_u64 v[146:147], s[12:13], 0, v[144:145]
	v_lshlrev_b64 v[220:221], 13, v[172:173]
	v_lshlrev_b64 v[222:223], 13, v[188:189]
	v_lshlrev_b64 v[224:225], 13, v[204:205]
	v_lshl_add_u64 v[168:169], v[146:147], 0, v[148:149]
	v_lshl_add_u64 v[184:185], v[146:147], 0, v[220:221]
	v_lshl_add_u64 v[200:201], v[146:147], 0, v[222:223]
	v_lshl_add_u64 v[216:217], v[146:147], 0, v[224:225]
	global_load_dwordx4 v[156:159], v[168:169], off
	global_load_dwordx4 v[160:163], v[168:169], off offset:64
	global_load_dwordx4 v[164:167], v[168:169], off offset:512
	s_nop 0
	global_load_dwordx4 v[168:171], v[168:169], off offset:576
	s_nop 0
	global_load_dwordx4 v[172:175], v[184:185], off
	global_load_dwordx4 v[176:179], v[184:185], off offset:64
	global_load_dwordx4 v[180:183], v[184:185], off offset:512
	s_nop 0
	global_load_dwordx4 v[184:187], v[184:185], off offset:576
	s_nop 0
	global_load_dwordx4 v[188:191], v[200:201], off
	global_load_dwordx4 v[192:195], v[200:201], off offset:64
	global_load_dwordx4 v[196:199], v[200:201], off offset:512
	s_nop 0
	global_load_dwordx4 v[200:203], v[200:201], off offset:576
	s_nop 0
	global_load_dwordx4 v[204:207], v[216:217], off
	global_load_dwordx4 v[208:211], v[216:217], off offset:64
	global_load_dwordx4 v[212:215], v[216:217], off offset:512
	s_nop 0
	global_load_dwordx4 v[216:219], v[216:217], off offset:576
	v_lshl_add_u64 v[226:227], s[28:29], 0, v[148:149]
	v_lshl_add_u64 v[224:225], s[28:29], 0, v[224:225]
	v_lshl_add_u64 v[226:227], v[226:227], 0, v[144:145]
	v_lshl_add_u64 v[220:221], s[28:29], 0, v[220:221]
	v_lshl_add_u64 v[222:223], s[28:29], 0, v[222:223]
	v_lshl_add_u64 v[224:225], v[224:225], 0, v[144:145]
	v_lshl_add_u64 v[220:221], v[220:221], 0, v[144:145]
	v_lshl_add_u64 v[222:223], v[222:223], 0, v[144:145]
	s_and_b64 vcc, exec, s[0:1]
	s_mov_b32 s52, s20
	s_mov_b32 s51, s50
	s_mov_b64 s[34:35], s[24:25]
	s_mov_b64 s[26:27], s[22:23]
	s_waitcnt vmcnt(0)
;     DI void operator()(const f32x4 (&acc)[2][2][4][2], const Unit& u, int wr, int wc, int fr, int fq) const {
;     ...
;         for (int ai = 0; ai < 2; ++ai) {
;             f32x4 xv[4][2][2];
; #pragma unroll
;             for (int m = 0; m < 4; ++m) { const size_t off = (size_t)(row0 + ai * HALF + m * 16) * DM + col0;
; #pragma unroll
;                 for (int bj = 0; bj < 2; ++bj)
; #pragma unroll
;                     for (int n = 0; n < 2; ++n) xv[m][bj][n] = *(const f32x4*)(X + off + bj * HALF + n * 16); }
; #pragma unroll
;             for (int m = 0; m < 4; ++m) { const size_t off = (size_t)(row0 + ai * HALF + m * 16) * DM + col0;
; #pragma unroll
;                 for (int bj = 0; bj < 2; ++bj)
; #pragma unroll
;                     for (int n = 0; n < 2; ++n) *(f32x4*)(C + off + bj * HALF + n * 16) = acc[ai][bj][m][n] + xv[m][bj][n]; }
;             asm volatile("" ::: "memory");
	v_pk_add_f32 v[126:127], v[126:127], v[158:159]
	v_pk_add_f32 v[124:125], v[124:125], v[156:157]
	v_pk_add_f32 v[122:123], v[122:123], v[162:163]
	v_pk_add_f32 v[120:121], v[120:121], v[160:161]
	v_pk_add_f32 v[106:107], v[106:107], v[166:167]
	v_pk_add_f32 v[70:71], v[70:71], v[214:215]
	v_pk_add_f32 v[68:69], v[68:69], v[212:213]
	v_pk_add_f32 v[66:67], v[66:67], v[218:219]
	v_pk_add_f32 v[64:65], v[64:65], v[216:217]
	v_pk_add_f32 v[104:105], v[104:105], v[164:165]
	v_pk_add_f32 v[98:99], v[98:99], v[170:171]
	v_pk_add_f32 v[96:97], v[96:97], v[168:169]
	v_pk_add_f32 v[118:119], v[118:119], v[174:175]
	v_pk_add_f32 v[116:117], v[116:117], v[172:173]
	v_pk_add_f32 v[114:115], v[114:115], v[178:179]
	v_pk_add_f32 v[112:113], v[112:113], v[176:177]
	v_pk_add_f32 v[90:91], v[90:91], v[182:183]
	v_pk_add_f32 v[88:89], v[88:89], v[180:181]
	v_pk_add_f32 v[86:87], v[86:87], v[186:187]
	v_pk_add_f32 v[84:85], v[84:85], v[184:185]
	v_pk_add_f32 v[110:111], v[110:111], v[190:191]
	v_pk_add_f32 v[108:109], v[108:109], v[188:189]
	v_pk_add_f32 v[102:103], v[102:103], v[194:195]
	v_pk_add_f32 v[100:101], v[100:101], v[192:193]
	v_pk_add_f32 v[78:79], v[78:79], v[198:199]
	v_pk_add_f32 v[76:77], v[76:77], v[196:197]
	v_pk_add_f32 v[74:75], v[74:75], v[202:203]
	v_pk_add_f32 v[72:73], v[72:73], v[200:201]
	v_pk_add_f32 v[94:95], v[94:95], v[206:207]
	v_pk_add_f32 v[92:93], v[92:93], v[204:205]
	v_pk_add_f32 v[82:83], v[82:83], v[210:211]
	v_pk_add_f32 v[80:81], v[80:81], v[208:209]
	global_store_dwordx4 v[226:227], v[124:127], off nt
	global_store_dwordx4 v[226:227], v[120:123], off offset:64 nt
	global_store_dwordx4 v[226:227], v[104:107], off offset:512 nt
	global_store_dwordx4 v[226:227], v[96:99], off offset:576 nt
	global_store_dwordx4 v[220:221], v[116:119], off nt
	global_store_dwordx4 v[220:221], v[112:115], off offset:64 nt
	global_store_dwordx4 v[220:221], v[88:91], off offset:512 nt
	global_store_dwordx4 v[220:221], v[84:87], off offset:576 nt
	global_store_dwordx4 v[222:223], v[108:111], off nt
	global_store_dwordx4 v[222:223], v[100:103], off offset:64 nt
	global_store_dwordx4 v[222:223], v[76:79], off offset:512 nt
	global_store_dwordx4 v[222:223], v[72:75], off offset:576 nt
	global_store_dwordx4 v[224:225], v[92:95], off nt
	global_store_dwordx4 v[224:225], v[80:83], off offset:64 nt
	global_store_dwordx4 v[224:225], v[68:71], off offset:512 nt
	global_store_dwordx4 v[224:225], v[64:67], off offset:576 nt
	v_lshl_add_u64 v[156:157], v[148:149], 0, s[8:9]
	v_lshl_add_u64 v[158:159], v[148:149], 0, s[14:15]
	v_lshl_add_u64 v[160:161], v[148:149], 0, s[16:17]
	v_lshl_add_u64 v[148:149], v[148:149], 0, s[18:19]
	v_lshl_add_u64 v[80:81], v[146:147], 0, v[156:157]
	v_lshl_add_u64 v[92:93], v[146:147], 0, v[158:159]
	v_lshl_add_u64 v[108:109], v[146:147], 0, v[160:161]
	v_lshl_add_u64 v[124:125], v[146:147], 0, v[148:149]
	global_load_dwordx4 v[64:67], v[80:81], off
	global_load_dwordx4 v[68:71], v[80:81], off offset:64
	global_load_dwordx4 v[72:75], v[80:81], off offset:512
	global_load_dwordx4 v[76:79], v[80:81], off offset:576
	s_nop 0
	global_load_dwordx4 v[80:83], v[92:93], off
	global_load_dwordx4 v[84:87], v[92:93], off offset:64
	global_load_dwordx4 v[88:91], v[92:93], off offset:512
	s_nop 0
	global_load_dwordx4 v[92:95], v[92:93], off offset:576
	s_nop 0
	global_load_dwordx4 v[96:99], v[108:109], off
	global_load_dwordx4 v[100:103], v[108:109], off offset:64
	global_load_dwordx4 v[104:107], v[108:109], off offset:512
	s_nop 0
	global_load_dwordx4 v[108:111], v[108:109], off offset:576
	s_nop 0
	global_load_dwordx4 v[112:115], v[124:125], off
	global_load_dwordx4 v[116:119], v[124:125], off offset:64
	global_load_dwordx4 v[120:123], v[124:125], off offset:512
	s_nop 0
	global_load_dwordx4 v[124:127], v[124:125], off offset:576
	v_lshl_add_u64 v[146:147], s[28:29], 0, v[156:157]
	v_lshl_add_u64 v[156:157], s[28:29], 0, v[158:159]
	v_lshl_add_u64 v[158:159], s[28:29], 0, v[160:161]
	v_lshl_add_u64 v[148:149], s[28:29], 0, v[148:149]
	v_lshl_add_u64 v[146:147], v[146:147], 0, v[144:145]
	v_lshl_add_u64 v[156:157], v[156:157], 0, v[144:145]
	v_lshl_add_u64 v[158:159], v[158:159], 0, v[144:145]
	v_lshl_add_u64 v[144:145], v[148:149], 0, v[144:145]
	s_waitcnt vmcnt(0)
	v_pk_add_f32 v[62:63], v[62:63], v[66:67]
	v_pk_add_f32 v[60:61], v[60:61], v[64:65]
	v_pk_add_f32 v[58:59], v[58:59], v[70:71]
	v_pk_add_f32 v[56:57], v[56:57], v[68:69]
	v_pk_add_f32 v[42:43], v[42:43], v[74:75]
	v_pk_add_f32 v[40:41], v[40:41], v[72:73]
	v_pk_add_f32 v[2:3], v[2:3], v[126:127]
	v_pk_add_f32 v[0:1], v[0:1], v[124:125]
	v_pk_add_f32 v[34:35], v[34:35], v[78:79]
	v_pk_add_f32 v[32:33], v[32:33], v[76:77]
	v_pk_add_f32 v[54:55], v[54:55], v[82:83]
	v_pk_add_f32 v[52:53], v[52:53], v[80:81]
	v_pk_add_f32 v[50:51], v[50:51], v[86:87]
	v_pk_add_f32 v[48:49], v[48:49], v[84:85]
	v_pk_add_f32 v[26:27], v[26:27], v[90:91]
	v_pk_add_f32 v[24:25], v[24:25], v[88:89]
	v_pk_add_f32 v[22:23], v[22:23], v[94:95]
	v_pk_add_f32 v[20:21], v[20:21], v[92:93]
	v_pk_add_f32 v[46:47], v[46:47], v[98:99]
	v_pk_add_f32 v[44:45], v[44:45], v[96:97]
	v_pk_add_f32 v[38:39], v[38:39], v[102:103]
	v_pk_add_f32 v[36:37], v[36:37], v[100:101]
	v_pk_add_f32 v[14:15], v[14:15], v[106:107]
	v_pk_add_f32 v[12:13], v[12:13], v[104:105]
	v_pk_add_f32 v[10:11], v[10:11], v[110:111]
	v_pk_add_f32 v[8:9], v[8:9], v[108:109]
	v_pk_add_f32 v[30:31], v[30:31], v[114:115]
	v_pk_add_f32 v[28:29], v[28:29], v[112:113]
	v_pk_add_f32 v[18:19], v[18:19], v[118:119]
	v_pk_add_f32 v[16:17], v[16:17], v[116:117]
	v_pk_add_f32 v[6:7], v[6:7], v[122:123]
	v_pk_add_f32 v[4:5], v[4:5], v[120:121]
	global_store_dwordx4 v[146:147], v[60:63], off nt
	global_store_dwordx4 v[146:147], v[56:59], off offset:64 nt
	global_store_dwordx4 v[146:147], v[40:43], off offset:512 nt
	global_store_dwordx4 v[146:147], v[32:35], off offset:576 nt
	global_store_dwordx4 v[156:157], v[52:55], off nt
	global_store_dwordx4 v[156:157], v[48:51], off offset:64 nt
	global_store_dwordx4 v[156:157], v[24:27], off offset:512 nt
	global_store_dwordx4 v[156:157], v[20:23], off offset:576 nt
	global_store_dwordx4 v[158:159], v[44:47], off nt
	global_store_dwordx4 v[158:159], v[36:39], off offset:64 nt
	global_store_dwordx4 v[158:159], v[12:15], off offset:512 nt
	global_store_dwordx4 v[158:159], v[8:11], off offset:576 nt
	global_store_dwordx4 v[144:145], v[28:31], off nt
	global_store_dwordx4 v[144:145], v[16:19], off offset:64 nt
	global_store_dwordx4 v[144:145], v[4:7], off offset:512 nt
	global_store_dwordx4 v[144:145], v[0:3], off offset:576 nt
	s_cbranch_vccz .LBB0_696
	s_waitcnt vmcnt(0)
	s_cmpk_gt_u32 s7, 0xff
	s_cbranch_scc1 .LBB0_709
	s_barrier
